# dense: K fragments in three register sets, reads three QK groups ahead (third set in v[66:73], -m straight from v[114:129])
# speedup vs baseline: 1.0081x; 1.0081x over previous
; #define SBAR() __builtin_amdgcn_sched_barrier(0)
; #define PK4(P, BASE, OUT) do { unsigned a0 = cvtpk(P[BASE + 0], P[BASE + 1]), a1 = cvtpk(P[BASE + 2], P[BASE + 3]);   \
;     unsigned b0 = cvtpk(P[BASE + 4], P[BASE + 5]), b1 = cvtpk(P[BASE + 6], P[BASE + 7]);                              \
;     u32x4 w = {a0, a1, b0, b1}; OUT = *reinterpret_cast<bf16x8*>(&w); } while (0)
; #define KRD(f, d0, kb) asm volatile("ds_read_b128 %0, %2 offset:%3\n\tds_read_b128 %1, %2 offset:%4" : "=&v"(f.a), "=&v"(f.b) : "v"((kb) + koff[(d0) & 3]), "i"(((d0) >> 2) * 128), "i"(((d0) >> 2) * 128 + 8192) : "memory")
; #define LW(n) do { asm volatile("s_waitcnt lgkmcnt(" #n ")" ::: "memory"); SBAR(); } while (0)
; __device__ __forceinline__ void finishSM(f32x16& p0, f32x16& p1, float alpha, float& l_reg, bf16x8& pa0, bf16x8& pa1, bf16x8& pa2, bf16x8& pa3) {
;   for (int r = 0; r < 16; ++r) p1[r] = __builtin_amdgcn_exp2f(p1[r]);
;   float ps = 0; for (int r = 0; r < 16; ++r) ps += p0[r]; for (int r = 0; r < 16; ++r) ps += p1[r];
;   { auto rr = __builtin_amdgcn_permlane32_swap(__float_as_uint(ps), __float_as_uint(ps), false, false);
;     ps = __uint_as_float(rr[0]) + __uint_as_float(rr[1]); }
;   l_reg = l_reg * alpha + ps;
;     ...
;   PK4(p0, 0, pa0); PK4(p0, 8, pa1); PK4(p1, 0, pa2); PK4(p1, 8, pa3);
;     ...
;       if (!grpB && t + 3 < NT) DMA(t + 3, (t + 3) & 3);
;       SBAR();
;       if (t + 1 < NT) {
;         const int kb_ = kbase0 + ((t + 1) & 3) * (int)SHM_K, vb_ = VBUF(t);
;         KFrag k0_, k1_; VFrag fa_, fb_;
;         KRD(k0_, 0, kb_); KRD(k1_, 1, kb_); pv_rd<0>(fa_, vb_);
;         if (MK_PREB && grpB) asm volatile("s_barrier" ::: "memory");
;     ...
;         LW(10); pA0 = __builtin_amdgcn_mfma_f32_32x32x16_bf16(k0_.a, qr[0], negm, 0, 0, 0); pA1 = __builtin_amdgcn_mfma_f32_32x32x16_bf16(k0_.b, qr[0], negm, 0, 0, 0); SBAR(); KRD(k0_, 2, kb_);
.LBB0_65:
	v_exp_f32_e32 v98, v98
	v_exp_f32_e32 v99, v99
	v_exp_f32_e32 v100, v100
	v_exp_f32_e32 v101, v101
	v_exp_f32_e32 v102, v102
	v_add_f32_e32 v162, 0, v98
	v_exp_f32_e32 v103, v103
	v_add_f32_e32 v162, v99, v162
	v_exp_f32_e32 v104, v104
	v_add_f32_e32 v162, v100, v162
	v_exp_f32_e32 v105, v105
	v_add_f32_e32 v162, v101, v162
	v_exp_f32_e32 v106, v106
	v_add_f32_e32 v162, v102, v162
	v_exp_f32_e32 v107, v107
	v_add_f32_e32 v162, v103, v162
	v_exp_f32_e32 v108, v108
	v_add_f32_e32 v162, v104, v162
	v_exp_f32_e32 v109, v109
	v_add_f32_e32 v162, v105, v162
	v_exp_f32_e32 v110, v110
	v_add_f32_e32 v162, v106, v162
	v_exp_f32_e32 v111, v111
	v_add_f32_e32 v162, v107, v162
	v_exp_f32_e32 v112, v112
	v_add_f32_e32 v162, v108, v162
	v_exp_f32_e32 v113, v113
	v_add_f32_e32 v162, v109, v162
	v_exp_f32_e32 v82, v82
	v_add_f32_e32 v162, v110, v162
	v_exp_f32_e32 v83, v83
	v_add_f32_e32 v162, v111, v162
	v_exp_f32_e32 v84, v84
	v_add_f32_e32 v162, v112, v162
	v_exp_f32_e32 v85, v85
	v_add_f32_e32 v162, v113, v162
	v_exp_f32_e32 v86, v86
	v_add_f32_e32 v162, v82, v162
	v_exp_f32_e32 v87, v87
	v_add_f32_e32 v162, v83, v162
	v_exp_f32_e32 v88, v88
	v_add_f32_e32 v162, v84, v162
	v_exp_f32_e32 v89, v89
	v_add_f32_e32 v162, v85, v162
	v_exp_f32_e32 v90, v90
	v_add_f32_e32 v162, v86, v162
	v_exp_f32_e32 v91, v91
	v_add_f32_e32 v162, v87, v162
	v_exp_f32_e32 v92, v92
	v_add_f32_e32 v162, v88, v162
	v_exp_f32_e32 v93, v93
	v_add_f32_e32 v162, v89, v162
	v_exp_f32_e32 v94, v94
	v_add_f32_e32 v162, v90, v162
	v_exp_f32_e32 v95, v95
	v_add_f32_e32 v162, v91, v162
	v_exp_f32_e32 v96, v96
	v_add_f32_e32 v162, v92, v162
	v_exp_f32_e32 v97, v97
	v_add_f32_e32 v162, v93, v162
	v_add_f32_e32 v162, v94, v162
	v_add_f32_e32 v162, v95, v162
	v_add_f32_e32 v162, v96, v162
	v_add_f32_e32 v243, v97, v162
	v_mov_b32_e32 v245, v243
	v_cvt_pk_bf16_f32 v166, v82, v83
	v_cndmask_b32_e64 v82, 0, 1, s[0:1]
	s_nop 0
	v_permlane32_swap_b32_e32 v243, v245
	v_cmp_ne_u32_e64 s[42:43], 1, v82
	s_andn2_b64 vcc, exec, s[0:1]
	v_cvt_pk_bf16_f32 v174, v98, v99
	v_cvt_pk_bf16_f32 v175, v100, v101
	v_cvt_pk_bf16_f32 v176, v102, v103
	v_cvt_pk_bf16_f32 v177, v104, v105
	v_cvt_pk_bf16_f32 v170, v106, v107
	v_cvt_pk_bf16_f32 v171, v108, v109
	v_cvt_pk_bf16_f32 v172, v110, v111
	v_cvt_pk_bf16_f32 v173, v112, v113
	v_cvt_pk_bf16_f32 v167, v84, v85
	v_cvt_pk_bf16_f32 v168, v86, v87
	v_cvt_pk_bf16_f32 v169, v88, v89
	v_cvt_pk_bf16_f32 v162, v90, v91
	v_cvt_pk_bf16_f32 v163, v92, v93
	v_cvt_pk_bf16_f32 v164, v94, v95
	v_cvt_pk_bf16_f32 v165, v96, v97
	s_cbranch_vccnz .LBB0_67
	s_add_i32 s15, s86, 0xc000
	s_and_b32 s15, s15, 0xc000
	s_add_i32 s84, s13, s15
	s_waitcnt vmcnt(4) lgkmcnt(0)
	s_barrier
	s_mov_b32 m0, s84
	s_add_i32 s15, s14, s15
	global_load_lds_dwordx4 v[74:75], off
	s_mov_b32 m0, s15
	s_nop 0
	global_load_lds_dwordx4 v[76:77], off
	s_add_i32 m0, s84, 0x400
	s_nop 0
	global_load_lds_dwordx4 v[78:79], off
	s_add_i32 m0, s15, 0x400
	s_nop 0
	global_load_lds_dwordx4 v[80:81], off
.LBB0_67:
	s_add_u32 s84, s86, 0x4000
	s_addc_u32 s85, s87, 0
	s_and_b32 s87, s84, 0xc000
	s_and_b32 s15, s86, 0xc000
	v_add_u32_e32 v248, s87, v239
	ds_read_b128 v[82:85], v248 offset:0
	ds_read_b128 v[202:205], v248 offset:0x2000
	v_add_u32_e32 v247, s87, v238
	ds_read_b128 v[198:201], v247 offset:0
	ds_read_b128 v[194:197], v247 offset:0x2000
	v_add_u32_e32 v217, s87, v237
	ds_read_b128 v[66:69], v217 offset:0
	ds_read_b128 v[70:73], v217 offset:0x2000
	v_add_u32_e32 v246, s15, v244
	ds_read_b64_tr_b16 v[190:191], v246 offset:0
	ds_read_b64_tr_b16 v[192:193], v246 offset:0x800
	ds_read_b64_tr_b16 v[186:187], v246 offset:0x1000
	ds_read_b64_tr_b16 v[188:189], v246 offset:0x1800
	ds_read_b64_tr_b16 v[182:183], v246 offset:0x2000
	ds_read_b64_tr_b16 v[184:185], v246 offset:0x2800
	ds_read_b64_tr_b16 v[178:179], v246 offset:0x3000
	ds_read_b64_tr_b16 v[180:181], v246 offset:0x3800
	v_add_u32_e32 v206, s87, v236
	s_and_b64 vcc, exec, s[44:45]
	s_cbranch_vccnz .LBB0_69
	s_barrier
; #define SBAR() __builtin_amdgcn_sched_barrier(0)
; #define KRD(f, d0, kb) asm volatile("ds_read_b128 %0, %2 offset:%3\n\tds_read_b128 %1, %2 offset:%4" : "=&v"(f.a), "=&v"(f.b) : "v"((kb) + koff[(d0) & 3]), "i"(((d0) >> 2) * 128), "i"(((d0) >> 2) * 128 + 8192) : "memory")
; #define QMM(f, d0) do { pA0 = __builtin_amdgcn_mfma_f32_32x32x16_bf16(f.a, qr[d0], pA0, 0, 0, 0); pA1 = __builtin_amdgcn_mfma_f32_32x32x16_bf16(f.b, qr[d0], pA1, 0, 0, 0); } while (0)
; #define LW(n) do { asm volatile("s_waitcnt lgkmcnt(" #n ")" ::: "memory"); SBAR(); } while (0)
; #define PP_BAR(VM) do { if (VM) { asm volatile("s_waitcnt vmcnt(4) lgkmcnt(0)\n\ts_barrier" ::: "memory"); } else { asm volatile("s_waitcnt vmcnt(0) lgkmcnt(0)\n\ts_barrier" ::: "memory"); } } while (0)
; #define PP_BAR_PLAIN() asm volatile("s_waitcnt lgkmcnt(0)\n\ts_barrier" ::: "memory")
;     ...
;         LW(10); pA0 = __builtin_amdgcn_mfma_f32_32x32x16_bf16(k0_.a, qr[0], negm, 0, 0, 0); pA1 = __builtin_amdgcn_mfma_f32_32x32x16_bf16(k0_.b, qr[0], negm, 0, 0, 0); SBAR(); KRD(k0_, 2, kb_);
;     ...
;         pA0 = f32x16{}; pA1 = f32x16{};
;         LW(10); QMM(k0_, 0); SBAR(); KRD(k0_, 2, kb_);
;     ...
;         LW(10); QMM(k1_, 1); SBAR(); KRD(k1_, 3, kb_);
;         LW(4);  pv_mm(o[0], fa_, pa0, pa1, pa2, pa3); SBAR(); pv_rd<1>(fb_, vb_);
;         LW(10); QMM(k0_, 2); SBAR(); KRD(k0_, 4, kb_);
;         LW(10); QMM(k1_, 3); SBAR(); KRD(k1_, 5, kb_);
;         LW(4);  pv_mm(o[1], fb_, pa0, pa1, pa2, pa3); SBAR(); pv_rd<2>(fa_, vb_);
;         LW(10); QMM(k0_, 4); SBAR(); KRD(k0_, 6, kb_);
;         LW(10); QMM(k1_, 5); SBAR(); KRD(k1_, 7, kb_);
;         LW(4);  pv_mm(o[2], fa_, pa0, pa1, pa2, pa3); SBAR(); pv_rd<3>(fb_, vb_);
;         LW(10); QMM(k0_, 6); SBAR();
;         LW(8);  QMM(k1_, 7); SBAR();
;         LW(0);  pv_mm(o[3], fb_, pa0, pa1, pa2, pa3);
;       } else pv_d0(o, VBUF(t), pa0, pa1, pa2, pa3);
;       if (t + 1 < NT) { if (grpB) PP_BAR(t + 3 < NT); else PP_BAR_PLAIN(); }
.LBB0_69:
	s_waitcnt lgkmcnt(12)
	v_mfma_f32_32x32x16_bf16 v[98:113], v[82:85], v[158:161], v[114:129]
	v_mfma_f32_32x32x16_bf16 v[82:97], v[202:205], v[158:161], v[114:129]
	ds_read_b128 v[250:253], v206 offset:0
	ds_read_b128 v[202:205], v206 offset:0x2000
	s_waitcnt lgkmcnt(12)
	v_mfma_f32_32x32x16_bf16 v[98:113], v[198:201], v[154:157], v[98:113]
	v_mfma_f32_32x32x16_bf16 v[82:97], v[194:197], v[154:157], v[82:97]
	ds_read_b128 v[198:201], v248 offset:0x80
	ds_read_b128 v[194:197], v248 offset:0x2080
	s_waitcnt lgkmcnt(4)
	v_mfma_f32_32x32x16_bf16 v[2:17], v[174:177], v[190:193], v[2:17]
	ds_read_b64_tr_b16 v[190:191], v246 offset:0x3200
	ds_read_b64_tr_b16 v[192:193], v246 offset:0x3a00
	v_mfma_f32_32x32x16_bf16 v[2:17], v[170:173], v[186:189], v[2:17]
	ds_read_b64_tr_b16 v[186:187], v246 offset:0x2200
	ds_read_b64_tr_b16 v[188:189], v246 offset:0x2a00
	v_mfma_f32_32x32x16_bf16 v[2:17], v[166:169], v[182:185], v[2:17]
	ds_read_b64_tr_b16 v[182:183], v246 offset:0x1200
	ds_read_b64_tr_b16 v[184:185], v246 offset:0x1a00
	v_mfma_f32_32x32x16_bf16 v[2:17], v[162:165], v[178:181], v[2:17]
	ds_read_b64_tr_b16 v[178:179], v246 offset:0x200
	ds_read_b64_tr_b16 v[180:181], v246 offset:0xa00
	v_mfma_f32_32x32x16_bf16 v[98:113], v[66:69], v[150:153], v[98:113]
	v_mfma_f32_32x32x16_bf16 v[82:97], v[70:73], v[150:153], v[82:97]
	ds_read_b128 v[66:69], v247 offset:0x80
	ds_read_b128 v[70:73], v247 offset:0x2080
	s_waitcnt lgkmcnt(12)
	v_mfma_f32_32x32x16_bf16 v[98:113], v[250:253], v[146:149], v[98:113]
	v_mfma_f32_32x32x16_bf16 v[82:97], v[202:205], v[146:149], v[82:97]
	ds_read_b128 v[250:253], v217 offset:0x80
	ds_read_b128 v[202:205], v217 offset:0x2080
	s_waitcnt lgkmcnt(4)
	v_mfma_f32_32x32x16_bf16 v[50:65], v[174:177], v[178:181], v[50:65]
	ds_read_b64_tr_b16 v[178:179], v246 offset:0x400
	ds_read_b64_tr_b16 v[180:181], v246 offset:0xc00
	v_mfma_f32_32x32x16_bf16 v[50:65], v[170:173], v[182:185], v[50:65]
	ds_read_b64_tr_b16 v[182:183], v246 offset:0x1400
	ds_read_b64_tr_b16 v[184:185], v246 offset:0x1c00
	v_mfma_f32_32x32x16_bf16 v[50:65], v[166:169], v[186:189], v[50:65]
	ds_read_b64_tr_b16 v[186:187], v246 offset:0x2400
	ds_read_b64_tr_b16 v[188:189], v246 offset:0x2c00
	v_mfma_f32_32x32x16_bf16 v[50:65], v[162:165], v[190:193], v[50:65]
	ds_read_b64_tr_b16 v[190:191], v246 offset:0x3400
	ds_read_b64_tr_b16 v[192:193], v246 offset:0x3c00
	v_mfma_f32_32x32x16_bf16 v[98:113], v[198:201], v[142:145], v[98:113]
	v_mfma_f32_32x32x16_bf16 v[82:97], v[194:197], v[142:145], v[82:97]
	ds_read_b128 v[198:201], v206 offset:0x80
	ds_read_b128 v[194:197], v206 offset:0x2080
	s_waitcnt lgkmcnt(12)
	v_mfma_f32_32x32x16_bf16 v[98:113], v[66:69], v[138:141], v[98:113]
	v_mfma_f32_32x32x16_bf16 v[82:97], v[70:73], v[138:141], v[82:97]
	s_waitcnt lgkmcnt(2)
	v_mfma_f32_32x32x16_bf16 v[34:49], v[174:177], v[178:181], v[34:49]
	ds_read_b64_tr_b16 v[178:179], v246 offset:0x600
	ds_read_b64_tr_b16 v[180:181], v246 offset:0xe00
	v_mfma_f32_32x32x16_bf16 v[34:49], v[170:173], v[182:185], v[34:49]
	ds_read_b64_tr_b16 v[182:183], v246 offset:0x1600
	ds_read_b64_tr_b16 v[184:185], v246 offset:0x1e00
	v_mfma_f32_32x32x16_bf16 v[34:49], v[166:169], v[186:189], v[34:49]
	ds_read_b64_tr_b16 v[186:187], v246 offset:0x2600
	ds_read_b64_tr_b16 v[188:189], v246 offset:0x2e00
	v_mfma_f32_32x32x16_bf16 v[34:49], v[162:165], v[190:193], v[34:49]
	ds_read_b64_tr_b16 v[190:191], v246 offset:0x3600
	ds_read_b64_tr_b16 v[192:193], v246 offset:0x3e00
	v_mfma_f32_32x32x16_bf16 v[98:113], v[250:253], v[134:137], v[98:113]
	v_mfma_f32_32x32x16_bf16 v[82:97], v[202:205], v[134:137], v[82:97]
	s_waitcnt lgkmcnt(8)
	v_mfma_f32_32x32x16_bf16 v[98:113], v[198:201], v[130:133], v[98:113]
	v_mfma_f32_32x32x16_bf16 v[82:97], v[194:197], v[130:133], v[82:97]
	s_waitcnt lgkmcnt(0)
	v_mfma_f32_32x32x16_bf16 v[18:33], v[174:177], v[178:181], v[18:33]
	v_mfma_f32_32x32x16_bf16 v[18:33], v[170:173], v[182:185], v[18:33]
	v_mfma_f32_32x32x16_bf16 v[18:33], v[166:169], v[186:189], v[18:33]
	v_mfma_f32_32x32x16_bf16 v[18:33], v[162:165], v[190:193], v[18:33]
	s_mov_b64 s[86:87], -1
	s_and_b64 vcc, exec, s[0:1]
	s_cbranch_vccz .LBB0_72
	s_waitcnt lgkmcnt(0)
	s_barrier
	s_cbranch_execz .LBB0_73
